# v22 + static s_setprio 1 for waves 0-3 during the phase 6 chunk scan
# baseline (speedup 1.0000x reference)
; #define LAS __attribute__((address_space(3)))
; __device__ __forceinline__ void scan_phase(const Params& p, int bid, int nblk, LAS unsigned char* lds) {
;     const int tid = threadIdx.x, lane = tid & 63, wid = __builtin_amdgcn_readfirstlane(tid >> 6), fr = lane & 15, fq = lane >> 4;
;     const bf16_t* wdc = (const bf16_t*)(p.ws + WS_WDC); const bf16_t* qd = (const bf16_t*)(p.ws + WS_QD); const bf16_t* kt = (const bf16_t*)(p.ws + WS_KT); const bf16_t* qk = (const bf16_t*)(p.ws + WS_QK);
;     const float* cdv = (const float*)(p.ws + WS_CD); const float* ub = p.out + OS_UB; float* obuf = p.out + OS_O;
;     for (int item = bid; item < 256; item += nblk) {
;         const int xcd = item & 7, iq = item >> 3, bh = xcd * 4 + (iq >> 3), sl = iq & 7, h = bh & 7, b = bh >> 3;
;         u32x4 r_wd[2], r_qd[2], r_kt[2], r_qk, r_ub;
;         auto gload = [&](int n) {
;             const size_t it = (size_t)(bh * 32 + n);
; #pragma unroll
;             for (int i = 0; i < 2; ++i) { const int ch = tid + 512 * i; r_wd[i] = *(const u32x4*)(wdc + it * 8192 + ch * 8); r_qd[i] = *(const u32x4*)(qd + it * 8192 + ch * 8); r_kt[i] = *(const u32x4*)(kt + it * 8192 + ch * 8); }
;             r_qk = *(const u32x4*)(qk + it * 4096 + tid * 8);
;             if (tid < 256) r_ub = *(const u32x4*)(ub + it * 8192 + (tid >> 2) * 128 + sl * 16 + (tid & 3) * 4);
;         };
;         auto lstore = [&](int buf) {
;             LAS unsigned char* B = lds + buf * SB_SIZE;
; #pragma unroll
;             for (int i = 0; i < 2; ++i) { const int ch = tid + 512 * i; const int r = ch >> 4, c8 = (ch & 15) * 8; *(LAS u32x4*)(B + SB_WD + r * 272 + c8 * 2) = r_wd[i]; *(LAS u32x4*)(B + SB_QD + r * 272 + c8 * 2) = r_qd[i];
;                 const int d = ch >> 3, t8 = (ch & 7) * 8; *(LAS u32x4*)(B + SB_KT + d * 144 + t8 * 2) = r_kt[i]; }
;             { const int r = tid >> 3, s8 = (tid & 7) * 8; *(LAS u32x4*)(B + SB_QK + r * 144 + s8 * 2) = r_qk; }
;             if (tid < 256) *(LAS u32x4*)(B + SB_UB + (tid >> 2) * 64 + (tid & 3) * 16) = r_ub;
;         };
;         __syncthreads();
;         gload(0);
;         for (int i = tid; i < 4352 / 4; i += 512) *(LAS unsigned*)(lds + SC_ST + i * 4) = 0u;
;         lstore(0);
;         f32x4 sacc = (f32x4){0.f, 0.f, 0.f, 0.f};
;         const float cdall = cdv[bh * 32 + (lane & 31)];
;         __syncthreads();
.LBB0_1064:
	s_cmp_lt_i32 s86, 7
	s_cselect_b64 s[4:5], -1, 0
	s_and_b64 s[6:7], s[4:5], s[6:7]
	s_andn2_b64 vcc, exec, s[6:7]
	s_cbranch_vccnz .LBB0_1104
	s_load_dwordx4 s[12:15], s[0:1], 0xc0
	v_and_b32_e32 v75, 63, v160
	s_cmpk_gt_i32 s2, 0xff
	v_and_b32_e32 v74, 31, v160
	v_readfirstlane_b32 s3, v160
	s_cbranch_scc1 .LBB0_1096
	s_waitcnt vmcnt(0)
	s_lshr_b32 s48, s3, 8
	s_cmp_lg_u32 s48, 0
	s_cbranch_scc1 .Lprio_scan
	s_setprio 1
.Lprio_scan:
	v_lshlrev_b32_e32 v1, 7, v160
	v_mov_b32_e32 v51, 0
	v_and_b32_e32 v50, 0x7e00, v1
	s_waitcnt lgkmcnt(0)
	v_lshl_add_u64 v[4:5], s[12:13], 0, v[50:51]
	s_mov_b64 s[8:9], 0x2200000
	v_add_u32_e32 v161, 0x200, v160
	s_add_u32 s10, s14, 0x7f38000
	v_lshl_add_u64 v[54:55], v[4:5], 0, s[8:9]
	s_movk_i32 s8, 0x110
	v_lshrrev_b32_e32 v6, 4, v161
	s_addc_u32 s11, s15, 0
	s_movk_i32 s9, 0x90
	v_mul_u32_u24_e32 v80, 0x110, v6
	v_mad_u32_u24 v8, v6, s8, 0
	v_lshrrev_b32_e32 v6, 3, v161
	s_add_i32 s16, 0, 0x21900
	v_and_b32_e32 v0, 15, v160
	v_mul_u32_u24_e32 v81, 0x90, v6
	v_mad_u32_u24 v9, v6, s9, 0
	v_mov_b32_e32 v6, s16
	s_add_i32 s16, 0, 0x20800
	v_mad_u32_u24 v85, v0, s9, v6
	v_mov_b32_e32 v6, s16
	v_lshlrev_b32_e32 v87, 2, v0
	s_add_i32 s16, 0, 0x1f800
	v_add_u32_e32 v11, s16, v87
	s_lshr_b32 s16, s3, 6
	v_mad_u32_u24 v86, v0, s8, v6
	v_lshrrev_b32_e32 v6, 4, v75
	s_cmpk_gt_u32 s3, 0xff
	v_lshlrev_b32_e32 v7, 3, v6
	v_lshlrev_b32_e32 v12, 2, v6
	s_cselect_b64 s[18:19], -1, 0
	s_lshl_b32 s20, s16, 4
	v_add_u32_e32 v88, v85, v7
	v_add_u32_e32 v13, v86, v7
	v_or_b32_e32 v7, s20, v0
	s_lshl_b32 s3, s16, 5
	s_and_b32 s16, s20, 48
	v_or_b32_e32 v6, s20, v12
	s_add_i32 s20, 0, 0x14800
	v_or_b32_e32 v14, s16, v0
	v_mov_b32_e32 v15, s20
	v_mad_u32_u24 v1, v166, s8, 0
	v_mul_lo_u32 v91, v7, s8
	v_mad_u32_u24 v15, v14, s8, v15
	s_add_i32 s8, 0, 0x10400
	v_mul_lo_u32 v89, v7, s9
	v_add_u32_e32 v16, s8, v91
	s_add_i32 s8, 0, 0x18c00
	v_mov_b32_e32 v7, v51
	v_add_u32_e32 v17, s8, v89
	s_add_i32 s8, 0, 0x1d400
	v_lshlrev_b32_e32 v48, 4, v160
	v_mov_b32_e32 v49, v51
	v_lshrrev_b32_e32 v5, 3, v160
	v_lshlrev_b32_e32 v93, 6, v6
	v_mov_b32_e32 v18, s8
	v_lshlrev_b64 v[6:7], 9, v[6:7]
	s_movk_i32 s8, 0x240
	v_lshl_add_u64 v[2:3], s[14:15], 0, v[48:49]
	v_mul_u32_u24_e32 v79, 0x90, v5
	v_mad_u32_u24 v5, v5, s9, 0
	v_mul_u32_u24_e32 v90, 0x110, v14
	v_mul_u32_u24_e32 v92, 0x90, v14
	v_mad_u32_u24 v14, v14, s9, v18
	v_lshl_add_u64 v[56:57], s[12:13], 0, v[6:7]
	v_sub_u32_e64 v6, s8, v160 clamp
	s_mov_b64 s[8:9], 0xe539000
	v_lshl_add_u64 v[60:61], v[2:3], 0, s[8:9]
	s_mov_b64 s[8:9], 0xf539000
	s_mov_b64 s[6:7], 0x11539000
	v_lshl_add_u64 v[62:63], v[2:3], 0, s[8:9]
	s_mov_b64 s[8:9], 0x10539000
	v_lshl_add_u64 v[52:53], v[2:3], 0, s[6:7]
	v_add_u32_e32 v6, 0x1ff, v6
	v_lshl_add_u64 v[64:65], v[2:3], 0, s[8:9]
	v_and_b32_e32 v2, 3, v160
	v_and_b32_e32 v82, 0x3fc0, v48
	v_lshrrev_b32_e32 v58, 9, v6
	s_lshl_b32 s36, s2, 2
	s_lshl_b32 s37, s96, 2
	v_lshl_or_b32 v50, v2, 4, v50
	s_movk_i32 s6, 0x100
	v_and_b32_e32 v4, 12, v184
	v_and_b32_e32 v76, 0xf0, v48
	s_mov_b32 s17, 0
	v_and_b32_e32 v78, 0x70, v48
	v_add_u32_e32 v10, 0, v82
	v_and_b32_e32 v83, 48, v48
	v_and_b32_e32 v84, 48, v160
	v_add_u32_e32 v6, 2, v58
	v_lshl_add_u64 v[2:3], s[12:13], 0, v[50:51]
	s_mov_b64 s[8:9], 0x2208000
	s_add_u32 s38, s14, 0x1153b000
	v_cmp_gt_u32_e64 s[6:7], s6, v160
	v_mul_u32_u24_e32 v77, 0x110, v166
	v_and_b32_e32 v94, 6, v6
	v_mov_b32_e32 v59, v58
	v_or_b32_e32 v95, s16, v12
	v_lshl_add_u64 v[66:67], v[2:3], 0, s[8:9]
	s_addc_u32 s39, s15, 0
	s_movk_i32 s40, 0x2000
	v_lshlrev_b32_e32 v68, 2, v4
	s_mov_b32 s21, 1
	v_add_u32_e32 v96, v1, v76
	v_add_u32_e32 v97, v5, v78
	v_add_u32_e32 v98, v8, v76
	v_add_u32_e32 v99, v9, v78
	v_add_u32_e32 v100, v10, v83
	v_lshlrev_b32_e32 v50, 2, v0
	s_mov_b64 s[22:23], 0x8000
	v_add_u32_e32 v101, v15, v84
	v_add_u32_e32 v102, v11, v93
	v_add_u32_e32 v103, v16, v84
	v_add_u32_e32 v104, v17, v84
	v_add_u32_e32 v105, v14, v84
	s_mov_b32 s20, s17
	v_add_u32_e32 v106, s3, v13
	s_mov_b32 s41, s2
	s_branch .LBB0_1068

; #define LAS __attribute__((address_space(3)))
; __device__ __forceinline__ float bf2f(unsigned short x) { return __uint_as_float(((unsigned)x) << 16); }
; __device__ __forceinline__ void scan_phase(const Params& p, int bid, int nblk, LAS unsigned char* lds) {
;     ...
;     __syncthreads();
;     {
;         const bf16_t* qn = (const bf16_t*)(p.ws + WS_QN); const bf16_t* kn = (const bf16_t*)(p.ws + WS_KN); const bf16_t* vv = (const bf16_t*)(p.ws + WS_VV);
;         const float* gbuf = (const float*)(p.ws + WS_G); const float* bbuf = (const float*)(p.ws + WS_BETA);
;         const int grp = tid >> 8, w4 = __builtin_amdgcn_readfirstlane(tid >> 6) & 3, j = w4 * 32 + (lane & 31), half = lane >> 5;
;         LAS float* qs = (LAS float*)lds + grp * 1024;
;         LAS float* ks = qs + 512;
;         const float scale = 0.08838834764831845f;
;         for (int it0 = bid * 2; it0 < 1024; it0 += nblk * 2) {
;             const int item = it0 + grp, sb = item >> 3, h = item & 7;
;             __syncthreads();
; #pragma unroll
;             for (int i = 0; i < 4; ++i) { const int idx = (tid & 255) + 256 * i, tk = idx >> 7, c = idx & 127, t = tk & 3; const size_t go = (size_t)(TP + sb * 4 + t) * 1024 + h * 128 + c;
;                 if (tk < 4) qs[t * 128 + c] = bf2f(qn[go]); else ks[t * 128 + c] = bf2f(kn[go]); }
;             float S[64];
;             const float* s0 = p.in[4] + (size_t)item * 16384 + (size_t)half * 64 * 128 + j;
; #pragma unroll
;             for (int i = 0; i < 64; ++i) S[i] = __builtin_nontemporal_load(s0 + i * 128);
.LBB0_1096:
	s_setprio 0
	s_cmpk_gt_i32 s2, 0x1ff
	v_readfirstlane_b32 s20, v160
	s_waitcnt vmcnt(0) lgkmcnt(0)
	s_barrier
	s_cbranch_scc1 .LBB0_1103
	s_add_u32 s8, s14, 0xa139000
	s_addc_u32 s9, s15, 0
	s_add_u32 s10, s14, 0xb239000
	s_addc_u32 s11, s15, 0
	s_add_u32 s16, s14, 0x7eb0000
	s_load_dwordx2 s[22:23], s[0:1], 0x20
	s_addc_u32 s17, s15, 0
	s_add_u32 s18, s14, 0x7ef4000
	v_lshrrev_b32_e32 v143, 8, v160
	v_mbcnt_lo_u32_b32 v7, -1, 0
	s_addc_u32 s19, s15, 0
	v_lshl_add_u32 v0, v143, 12, 0
	v_lshrrev_b32_e32 v1, 5, v75
	v_and_b32_e32 v2, 0x80, v160
	v_and_b32_e32 v4, 0x7f, v160
	s_lshr_b32 s20, s20, 1
	v_mbcnt_hi_u32_b32 v7, -1, v7
	s_lshl_b32 s3, s2, 1
	v_lshl_add_u32 v5, v4, 2, v0
	v_lshl_add_u32 v144, v1, 8, v0
	s_lshl_b32 s26, s96, 1
	v_lshlrev_b32_e32 v0, 2, v2
	s_and_b32 s20, s20, 0x60
	v_and_b32_e32 v9, 64, v7
	v_bfe_u32 v145, v160, 7, 1
	v_add_u32_e32 v146, v5, v0
	v_or_b32_e32 v0, 0x100, v2
	v_lshlrev_b32_e32 v64, 15, v1
	v_mov_b32_e32 v65, 0
	v_or_b32_e32 v149, s20, v74
	v_xor_b32_e32 v8, 32, v7
	v_add_u32_e32 v9, 64, v9
	s_add_u32 s14, s14, 0xd339000
	v_lshrrev_b32_e32 v147, 7, v0
	v_or_b32_e32 v148, 2, v145
	s_waitcnt lgkmcnt(0)
	v_lshl_add_u64 v[0:1], s[22:23], 0, v[64:65]
	v_lshl_add_u64 v[2:3], s[12:13], 0, v[64:65]
	v_cmp_lt_i32_e32 vcc, v8, v9
	v_lshlrev_b32_e32 v64, 2, v149
	s_addc_u32 s15, s15, 0
	v_lshlrev_b32_e32 v6, 9, v148
	v_cndmask_b32_e32 v7, v7, v8, vcc
	v_lshl_add_u64 v[66:67], v[0:1], 0, v[64:65]
	v_lshl_add_u64 v[0:1], v[2:3], 0, v[64:65]
	s_mov_b64 s[20:21], 0x4660000
	s_add_u32 s12, s12, 0x2000000
	v_cmp_gt_u32_e64 s[6:7], 32, v75
	v_lshlrev_b32_e32 v150, 2, v7
	v_lshl_add_u64 v[68:69], v[0:1], 0, s[20:21]
	v_add_u16_e32 v151, s3, v143
	s_addc_u32 s13, s13, 0
	s_movk_i32 s27, 0x2000
	v_lshlrev_b32_e32 v152, 1, v4
	v_add_u32_e32 v153, v5, v6
	s_movk_i32 s28, 0x1000
	s_movk_i32 s29, 0x3000
	s_movk_i32 s30, 0x4000
	s_movk_i32 s31, 0x5000
	s_movk_i32 s34, 0x6000
	s_movk_i32 s35, 0x7000
	s_movk_i32 s36, 0xffe0
	s_mov_b64 s[20:21], 0x800
	s_mov_b64 s[22:23], 0x1000
	s_branch .LBB0_1099
